# XCD barrier: the globally last arriver bumps all eight per-XCD generation words itself (per-XCD last arrivers no longer forward the release)
# speedup vs baseline: 1.0087x; 1.0087x over previous
.LBB0_85:
	s_or_b64 exec, exec, s[8:9]
	s_and_saveexec_b64 s[4:5], s[12:13]
	s_cbranch_execz .LBB0_87
	v_mov_b32_e32 v2, 1
	global_atomic_add v[0:1], v2, off
	v_add_co_u32_e32 v4, vcc, 0xffffef00, v0
	s_nop 1
	v_addc_co_u32_e32 v5, vcc, -1, v1, vcc
	global_atomic_add v[4:5], v2, off
	global_atomic_add v[4:5], v2, off offset:256
	global_atomic_add v[4:5], v2, off offset:512
	global_atomic_add v[4:5], v2, off offset:768
	global_atomic_add v[4:5], v2, off offset:1024
	global_atomic_add v[4:5], v2, off offset:1280
	global_atomic_add v[4:5], v2, off offset:1536
	global_atomic_add v[4:5], v2, off offset:1792
.LBB0_87:
	s_or_b64 exec, exec, s[4:5]
	s_mov_b64 s[4:5], exec
	v_mbcnt_lo_u32_b32 v0, s4, 0
	v_mbcnt_hi_u32_b32 v0, s5, v0
	v_cmp_eq_u32_e32 vcc, 0, v0
	s_waitcnt vmcnt(0)
	s_and_saveexec_b64 s[8:9], vcc
	s_cbranch_execz .LBB0_89
	s_bcnt1_i32_b64 s3, s[4:5]
	v_mov_b32_e32 v0, 0x2000
	v_mov_b32_e32 v1, s3
.LBB0_89:
	s_or_b64 exec, exec, s[8:9]
	buffer_inv sc1
	s_waitcnt vmcnt(0)

.LBB0_246:
	s_or_b64 exec, exec, s[4:5]
	s_mov_b64 s[4:5], exec
	v_mbcnt_lo_u32_b32 v0, s4, 0
	v_mbcnt_hi_u32_b32 v0, s5, v0
	v_cmp_eq_u32_e32 vcc, 0, v0
	s_waitcnt vmcnt(0)
	s_and_saveexec_b64 s[8:9], vcc
	s_cbranch_execz .LBB0_248
	s_bcnt1_i32_b64 s3, s[4:5]
	v_mov_b32_e32 v0, 0x2000
	v_mov_b32_e32 v1, s3
.LBB0_248:
	s_or_b64 exec, exec, s[8:9]
	buffer_inv sc1
	s_waitcnt vmcnt(0)

.LBB0_301:
	s_or_b64 exec, exec, s[4:5]
	s_mov_b64 s[4:5], exec
	v_mbcnt_lo_u32_b32 v0, s4, 0
	v_mbcnt_hi_u32_b32 v0, s5, v0
	v_cmp_eq_u32_e32 vcc, 0, v0
	s_waitcnt vmcnt(0)
	s_and_saveexec_b64 s[8:9], vcc
	s_cbranch_execz .LBB0_303
	s_bcnt1_i32_b64 s3, s[4:5]
	v_mov_b32_e32 v0, 0x2000
	v_mov_b32_e32 v1, s3
.LBB0_303:
	s_or_b64 exec, exec, s[8:9]
	buffer_inv sc1
	s_waitcnt vmcnt(0)

.LBB0_408:
	s_or_b64 exec, exec, s[4:5]
	s_mov_b64 s[4:5], exec
	v_mbcnt_lo_u32_b32 v0, s4, 0
	v_mbcnt_hi_u32_b32 v0, s5, v0
	v_cmp_eq_u32_e32 vcc, 0, v0
	s_waitcnt vmcnt(0)
	s_and_saveexec_b64 s[8:9], vcc
	s_cbranch_execz .LBB0_410
	s_bcnt1_i32_b64 s3, s[4:5]
	v_mov_b32_e32 v0, 0x2000
	v_mov_b32_e32 v1, s3
.LBB0_410:
	s_or_b64 exec, exec, s[8:9]
	buffer_inv sc1
	s_waitcnt vmcnt(0)

.LBB0_629:
	s_or_b64 exec, exec, s[14:15]
	s_and_saveexec_b64 s[8:9], s[16:17]
	s_cbranch_execz .LBB0_631
	global_atomic_add v[0:1], v220, off
	v_add_co_u32_e32 v4, vcc, 0xffffef00, v0
	s_nop 1
	v_addc_co_u32_e32 v5, vcc, -1, v1, vcc
	global_atomic_add v[4:5], v220, off
	global_atomic_add v[4:5], v220, off offset:256
	global_atomic_add v[4:5], v220, off offset:512
	global_atomic_add v[4:5], v220, off offset:768
	global_atomic_add v[4:5], v220, off offset:1024
	global_atomic_add v[4:5], v220, off offset:1280
	global_atomic_add v[4:5], v220, off offset:1536
	global_atomic_add v[4:5], v220, off offset:1792
.LBB0_631:
	s_or_b64 exec, exec, s[8:9]
	s_mov_b64 s[8:9], exec
	v_mbcnt_lo_u32_b32 v0, s8, 0
	v_mbcnt_hi_u32_b32 v0, s9, v0
	v_cmp_eq_u32_e32 vcc, 0, v0
	s_waitcnt vmcnt(0)
	s_and_saveexec_b64 s[12:13], vcc
	s_cbranch_execz .LBB0_633
	s_bcnt1_i32_b64 s0, s[8:9]
	v_mov_b32_e32 v0, s0
.LBB0_633:
	s_or_b64 exec, exec, s[12:13]
	buffer_inv sc1
	s_waitcnt vmcnt(0)

.LBB0_739:
	s_or_b64 exec, exec, s[8:9]
	s_mov_b64 s[8:9], exec
	v_mbcnt_lo_u32_b32 v0, s8, 0
	v_mbcnt_hi_u32_b32 v0, s9, v0
	v_cmp_eq_u32_e32 vcc, 0, v0
	s_waitcnt vmcnt(0)
	s_and_saveexec_b64 s[12:13], vcc
	s_cbranch_execz .LBB0_741
	s_bcnt1_i32_b64 s0, s[8:9]
	v_mov_b32_e32 v0, s0
.LBB0_741:
	s_or_b64 exec, exec, s[12:13]
	buffer_inv sc1
	s_waitcnt vmcnt(0)

.LBB0_896:
	s_or_b64 exec, exec, s[8:9]
	s_mov_b64 s[8:9], exec
	v_mbcnt_lo_u32_b32 v0, s8, 0
	v_mbcnt_hi_u32_b32 v0, s9, v0
	v_cmp_eq_u32_e32 vcc, 0, v0
	s_waitcnt vmcnt(0)
	s_and_saveexec_b64 s[12:13], vcc
	s_cbranch_execz .LBB0_898
	s_bcnt1_i32_b64 s0, s[8:9]
	v_mov_b32_e32 v0, s0
.LBB0_898:
	s_or_b64 exec, exec, s[12:13]
	buffer_inv sc1
	s_waitcnt vmcnt(0)

.LBB0_966:
	s_or_b64 exec, exec, s[8:9]
	s_mov_b64 s[8:9], exec
	v_mbcnt_lo_u32_b32 v0, s8, 0
	v_mbcnt_hi_u32_b32 v0, s9, v0
	v_cmp_eq_u32_e32 vcc, 0, v0
	s_waitcnt vmcnt(0)
	s_and_saveexec_b64 s[12:13], vcc
	s_cbranch_execz .LBB0_968
	s_bcnt1_i32_b64 s0, s[8:9]
	v_mov_b32_e32 v0, s0
.LBB0_968:
	s_or_b64 exec, exec, s[12:13]
	buffer_inv sc1
	s_waitcnt vmcnt(0)

.LBB0_1033:
	s_or_b64 exec, exec, s[8:9]
	s_mov_b64 s[8:9], exec
	v_mbcnt_lo_u32_b32 v0, s8, 0
	v_mbcnt_hi_u32_b32 v0, s9, v0
	v_cmp_eq_u32_e32 vcc, 0, v0
	s_waitcnt vmcnt(0)
	s_and_saveexec_b64 s[12:13], vcc
	s_cbranch_execz .LBB0_1035
	s_bcnt1_i32_b64 s0, s[8:9]
	v_mov_b32_e32 v0, s0
.LBB0_1035:
	s_or_b64 exec, exec, s[12:13]
	buffer_inv sc1
	s_waitcnt vmcnt(0)

.LBB0_1214:
	s_or_b64 exec, exec, s[8:9]
	s_mov_b64 s[8:9], exec
	v_mbcnt_lo_u32_b32 v0, s8, 0
	v_mbcnt_hi_u32_b32 v0, s9, v0
	v_cmp_eq_u32_e32 vcc, 0, v0
	s_waitcnt vmcnt(0)
	s_and_saveexec_b64 s[12:13], vcc
	s_cbranch_execz .LBB0_1216
	s_bcnt1_i32_b64 s0, s[8:9]
	v_mov_b32_e32 v0, s0
.LBB0_1216:
	s_or_b64 exec, exec, s[12:13]
	buffer_inv sc1
	s_waitcnt vmcnt(0)

.LBB0_1304:
	s_or_b64 exec, exec, s[18:19]
	s_and_saveexec_b64 s[12:13], s[20:21]
	s_cbranch_execz .LBB0_1306
	global_atomic_add v[0:1], v220, off
	v_add_co_u32_e32 v4, vcc, 0xffffef00, v0
	s_nop 1
	v_addc_co_u32_e32 v5, vcc, -1, v1, vcc
	global_atomic_add v[4:5], v220, off
	global_atomic_add v[4:5], v220, off offset:256
	global_atomic_add v[4:5], v220, off offset:512
	global_atomic_add v[4:5], v220, off offset:768
	global_atomic_add v[4:5], v220, off offset:1024
	global_atomic_add v[4:5], v220, off offset:1280
	global_atomic_add v[4:5], v220, off offset:1536
	global_atomic_add v[4:5], v220, off offset:1792
.LBB0_1306:
	s_or_b64 exec, exec, s[12:13]
	s_mov_b64 s[12:13], exec
	v_mbcnt_lo_u32_b32 v0, s12, 0
	v_mbcnt_hi_u32_b32 v0, s13, v0
	v_cmp_eq_u32_e32 vcc, 0, v0
	s_waitcnt vmcnt(0)
	s_and_saveexec_b64 s[16:17], vcc
	s_cbranch_execz .LBB0_1308
	s_bcnt1_i32_b64 s0, s[12:13]
	v_mov_b32_e32 v0, s0
.LBB0_1308:
	s_or_b64 exec, exec, s[16:17]
	buffer_inv sc1
	s_waitcnt vmcnt(0)

.LBB0_1656:
	s_bcnt1_i32_b64 s0, s[8:9]
	v_mov_b32_e32 v0, s0
	s_getpc_b64 s[98:99]
